# combo8 + 40 bytes of padding after the attention code (K-loop code placement search)
# baseline (speedup 1.0000x reference)
.LBB0_599:
	s_nop 0
	s_nop 0
	s_nop 0
	s_nop 0
	s_nop 0
	s_nop 0
	s_nop 0
	s_nop 0
	s_nop 0
	s_nop 0
	s_mov_b32 s8, -1
	s_add_u32 s10, s18, 0x35600000
	v_mbcnt_lo_u32_b32 v0, s8, 0
	v_mbcnt_hi_u32_b32 v0, s8, v0
	v_add_u32_e32 v0, s76, v0
	v_readlane_b32 s8, v254, 25
	v_and_b32_e32 v72, 0xff, v0
	s_addc_u32 s11, s19, 0
	v_add_u32_e32 v35, s8, v0
	v_readfirstlane_b32 s14, v72
	s_mov_b32 s8, 0x80000
	s_mov_b64 s[12:13], -1
	s_cmp_gt_u32 s14, 63
	v_cmp_gt_i32_e64 s[8:9], s8, v35
	s_cbranch_scc0 .LBB0_618
	s_lshr_b32 s14, s14, 6
	s_cmp_lt_i32 s14, 2
	s_cbranch_scc1 .LBB0_612
	s_cmp_lg_u32 s14, 2
	s_cbranch_scc0 .LBB0_606
	s_and_saveexec_b64 s[12:13], s[8:9]
	s_movk_i32 s20, 0x800
	s_movk_i32 s21, 0x7ff
	s_movk_i32 s22, 0x6000
	s_mov_b32 s23, 0xd000
	s_mov_b32 s27, 0x13000
	s_movk_i32 s28, 0x7fe
	s_movk_i32 s34, 0x7fd
	s_mov_b32 s35, 0x77fff
	s_mov_b64 s[42:43], 0x1800
	s_cbranch_execz .LBB0_605
	v_lshlrev_b32_e32 v2, 3, v72
	v_lshlrev_b32_e32 v0, 4, v72
	v_lshl_add_u64 v[68:69], s[10:11], 0, v[0:1]
	s_mov_b64 s[14:15], 0
	v_lshlrev_b32_e32 v0, 1, v2
	v_mov_b32_e32 v73, v35
